# SB attention cross-unit prefetch: next unit's first Q/K/V loads issued at the start of the current unit into a second register set, copied in at the unit boundary (on top of noprio + SW sink table + S
# baseline (speedup 1.0000x reference)
; __device__ __forceinline__ unsigned cvtpk(float lo, float hi) { f32x2_t v = {lo, hi}; bf16x2_t b = __builtin_convertvector(v, bf16x2_t); return __builtin_bit_cast(unsigned, b); }
; #define SBW_LOAD(sb_) do { const bf16* kp_ = Kh + (size_t)(32 * (sb_) + vkg) * 64 + 8 * vdc; \
;             _Pragma("unroll") for (int j_ = 0; j_ < 4; ++j_) kn[j_] = *(const bf16x8*)(kp_ + (size_t)(8 * j_) * 64); \
;             _Pragma("unroll") for (int i_ = 0; i_ < 4; ++i_) vreg[i_] = *(const v4u*)(Vh + (size_t)(32 * (sb_) + 4 * vkg + i_) * 64 + 8 * vdc); } while (0)
; __device__ __forceinline__ void sb_attn(const bf16* QKV, bf16* O, LAS unsigned char* lds, int tid) {
;     ...
;     for (int u = gw; u < BATCH * 16 * (SEQ / 32); u += NGW) {
;         const int qblk = u & 127, bh = u >> 7, b = bh >> 4, h = bh & 15;
;         const size_t tok0 = (size_t)b * SEQ;
;         const int qr0 = qblk * 32, qpos = qr0 + l32;
;         bf16x8 qf[4], kn[4]; v4u vreg[4];
;         const bf16* const Qh = QKV + (size_t)(b * 48 + h) * SEQ * 64; const bf16* const Kh = QKV + (size_t)(b * 48 + 16 + h) * SEQ * 64; const bf16* const Vh = QKV + (size_t)(b * 48 + 32 + h) * SEQ * 64;
;         { const bf16* qp = Qh + (size_t)(qr0 + l32) * 64 + 8 * hi;
; #pragma unroll
;           for (int ks = 0; ks < 4; ++ks) qf[ks] = *(const bf16x8*)(qp + 16 * ks); }
;     ...
;         SBW_LOAD(qblk);
;     ...
;         { bf16* op = O + (tok0 + qr0 + l32) * D + h * 64 + 4 * hi;
; #pragma unroll
;           for (int g = 0; g < 4; ++g) {
;               const u32x2 a = {cvtpk(o0[4 * g], o0[4 * g + 1]), cvtpk(o0[4 * g + 2], o0[4 * g + 3])}, c = {cvtpk(o1[4 * g], o1[4 * g + 1]), cvtpk(o1[4 * g + 2], o1[4 * g + 3])};
;               *(u32x2*)(op + 8 * g) = a; *(u32x2*)(op + 32 + 8 * g) = c; } }
.LBB0_192:
	s_ashr_i32 s7, s6, 31
	s_lshl_b64 s[6:7], s[6:7], 12
	s_or_b32 s6, s6, s11
	v_mov_b32_e32 v33, s7
	v_or_b32_e32 v32, s6, v96
	v_lshlrev_b64 v[32:33], 11, v[32:33]
	v_lshl_add_u64 v[32:33], s[92:93], 0, v[32:33]
	s_lshl_b32 s88, s10, 7
	v_lshl_add_u64 v[32:33], v[32:33], 0, s[88:89]
	v_mov_b32_e32 v107, v157
	v_lshl_add_u64 v[32:33], v[32:33], 0, v[106:107]
	v_lshl_add_u64 v[32:33], v[32:33], 0, v[106:107]
	v_cvt_pk_bf16_f32 v16, v16, v17
	v_cvt_pk_bf16_f32 v17, v18, v19
	v_cvt_pk_bf16_f32 v18, v20, v21
	v_cvt_pk_bf16_f32 v19, v22, v23
	v_cvt_pk_bf16_f32 v20, v24, v25
	v_cvt_pk_bf16_f32 v21, v26, v27
	v_cvt_pk_bf16_f32 v22, v28, v29
	v_cvt_pk_bf16_f32 v23, v30, v31
	v_cvt_pk_bf16_f32 v0, v0, v1
	v_cvt_pk_bf16_f32 v1, v2, v3
	v_cvt_pk_bf16_f32 v2, v4, v5
	v_cvt_pk_bf16_f32 v3, v6, v7
	v_cvt_pk_bf16_f32 v4, v8, v9
	v_cvt_pk_bf16_f32 v5, v10, v11
	v_cvt_pk_bf16_f32 v6, v12, v13
	v_cvt_pk_bf16_f32 v7, v14, v15
	s_add_i32 s8, s8, s67
	s_add_i32 s9, s9, s67
	s_nop 1
	v_permlane32_swap_b32_e32 v16, v18
	v_permlane32_swap_b32_e32 v17, v19
	v_permlane32_swap_b32_e32 v20, v22
	v_permlane32_swap_b32_e32 v21, v23
	v_permlane32_swap_b32_e32 v0, v2
	v_permlane32_swap_b32_e32 v1, v3
	v_permlane32_swap_b32_e32 v4, v6
	v_permlane32_swap_b32_e32 v5, v7
	s_cmpk_gt_i32 s8, 0x3fff
	s_cbranch_scc1 .Lsb_last
	global_store_dwordx4 v[32:33], v[16:19], off
	global_store_dwordx4 v[32:33], v[20:23], off offset:32
	global_store_dwordx4 v[32:33], v[0:3], off offset:64
	global_store_dwordx4 v[32:33], v[4:7], off offset:96
	s_ashr_i32 s6, s8, 11
	s_bfe_u32 s10, s8, 0x40007
	s_mul_i32 s18, s6, 48
	s_and_b32 s7, s8, 0x7f
	s_lshl_b32 s11, s7, 5
	s_add_i32 s12, s18, 32
	s_or_b32 s14, s18, s10
	s_add_i32 s14, s14, 16
	s_ashr_i32 s15, s14, 31
	s_lshl_b64 s[14:15], s[14:15], 19
	s_add_u32 s14, s90, s14
	s_addc_u32 s15, s91, s15
	s_or_b32 s18, s12, s10
	s_ashr_i32 s19, s18, 31
	s_lshl_b64 s[18:19], s[18:19], 19
	v_or_b32_e32 v16, s11, v96
	v_lshl_add_u64 v[0:1], v[98:99], 0, s[18:19]
	v_mov_b32_e32 v105, v157
	v_mov_b32_e32 v103, v157
	v_lshl_add_u64 v[108:109], s[14:15], 0, v[104:105]
	s_waitcnt vmcnt(4)
	v_mov_b32_e32 v48, v128
	v_mov_b32_e32 v49, v129
	v_mov_b32_e32 v50, v130
	v_mov_b32_e32 v51, v131
	v_mov_b32_e32 v52, v132
	v_mov_b32_e32 v53, v133
	v_mov_b32_e32 v54, v134
	v_mov_b32_e32 v55, v135
	v_mov_b32_e32 v56, v136
	v_mov_b32_e32 v57, v137
	v_mov_b32_e32 v58, v138
	v_mov_b32_e32 v59, v139
	v_mov_b32_e32 v60, v140
	v_mov_b32_e32 v61, v141
	v_mov_b32_e32 v62, v142
	v_mov_b32_e32 v63, v143
	v_mov_b32_e32 v64, v144
	v_mov_b32_e32 v65, v145
	v_mov_b32_e32 v66, v146
	v_mov_b32_e32 v67, v147
	v_mov_b32_e32 v68, v148
	v_mov_b32_e32 v69, v149
	v_mov_b32_e32 v70, v150
	v_mov_b32_e32 v71, v151
	v_mov_b32_e32 v72, v152
	v_mov_b32_e32 v73, v153
	v_mov_b32_e32 v74, v154
	v_mov_b32_e32 v75, v155
	v_mov_b32_e32 v76, v172
	v_mov_b32_e32 v77, v173
	v_mov_b32_e32 v78, v174
	v_mov_b32_e32 v79, v175
	v_mov_b32_e32 v80, v176
	v_mov_b32_e32 v81, v177
	v_mov_b32_e32 v82, v178
	v_mov_b32_e32 v83, v179
	v_mov_b32_e32 v84, v180
	v_mov_b32_e32 v85, v181
	v_mov_b32_e32 v86, v182
	v_mov_b32_e32 v87, v183
	v_mov_b32_e32 v88, v184
	v_mov_b32_e32 v89, v185
	v_mov_b32_e32 v90, v186
	v_mov_b32_e32 v91, v187
	v_mov_b32_e32 v92, v188
	v_mov_b32_e32 v93, v189
	v_mov_b32_e32 v94, v190
	v_mov_b32_e32 v95, v191
	s_add_i32 s13, s8, s67
	s_cmpk_gt_i32 s13, 0x3fff
	s_cselect_b32 s13, s8, s13
	s_ashr_i32 s16, s13, 11
	s_bfe_u32 s17, s13, 0x40007
	s_mul_i32 s16, s16, 48
	s_and_b32 s13, s13, 0x7f
	s_lshl_b32 s13, s13, 5
	s_or_b32 s18, s16, s17
	s_ashr_i32 s19, s18, 31
	s_lshl_b64 s[14:15], s[18:19], 19
	s_add_u32 s14, s90, s14
	s_addc_u32 s15, s91, s15
	v_or_b32_e32 v246, s13, v96
	v_lshlrev_b32_e32 v156, 7, v246
	v_lshl_add_u64 v[244:245], s[14:15], 0, v[156:157]
	v_lshl_add_u64 v[244:245], v[244:245], 0, v[102:103]
	global_load_dwordx4 v[128:131], v[244:245], off
	global_load_dwordx4 v[132:135], v[244:245], off offset:32
	global_load_dwordx4 v[136:139], v[244:245], off offset:64
	global_load_dwordx4 v[140:143], v[244:245], off offset:96
	s_add_i32 s18, s18, 16
	s_ashr_i32 s19, s18, 31
	s_lshl_b64 s[14:15], s[18:19], 19
	s_add_u32 s14, s90, s14
	s_addc_u32 s15, s91, s15
	v_or_b32_e32 v247, s13, v97
	v_lshlrev_b32_e32 v156, 7, v247
	v_lshl_add_u64 v[244:245], s[14:15], 0, v[156:157]
	v_lshl_add_u64 v[244:245], v[244:245], 0, v[104:105]
	global_load_dwordx4 v[144:147], v[244:245], off
	global_load_dwordx4 v[148:151], v[244:245], off offset:1024
	global_load_dwordx4 v[152:155], v[244:245], off offset:2048
	global_load_dwordx4 v[172:175], v[244:245], off offset:3072
	s_add_i32 s18, s16, 32
	s_or_b32 s18, s18, s17
	s_ashr_i32 s19, s18, 31
	s_lshl_b64 s[18:19], s[18:19], 19
	v_lshl_add_u64 v[244:245], v[98:99], 0, s[18:19]
	v_or_b32_e32 v247, s13, v112
	v_lshlrev_b32_e32 v156, 7, v247
	v_lshl_add_u64 v[248:249], v[244:245], 0, v[156:157]
	global_load_dwordx4 v[176:179], v[248:249], off
	global_load_dwordx4 v[180:183], v[248:249], off offset:128
	global_load_dwordx4 v[184:187], v[248:249], off offset:256
	global_load_dwordx4 v[188:191], v[248:249], off offset:384
	s_cmp_eq_u32 s7, 0
	s_branch .Lsb_cont
.Lsb_last:
	global_store_dwordx4 v[32:33], v[16:19], off
	global_store_dwordx4 v[32:33], v[20:23], off offset:32
	global_store_dwordx4 v[32:33], v[0:3], off offset:64
	global_store_dwordx4 v[32:33], v[4:7], off offset:96
	s_branch .LBB0_200
; #define LAS __attribute__((address_space(3)))
; #define SBW_LOAD(sb_) do { const bf16* kp_ = Kh + (size_t)(32 * (sb_) + vkg) * 64 + 8 * vdc; \
;             _Pragma("unroll") for (int j_ = 0; j_ < 4; ++j_) kn[j_] = *(const bf16x8*)(kp_ + (size_t)(8 * j_) * 64); \
;             _Pragma("unroll") for (int i_ = 0; i_ < 4; ++i_) vreg[i_] = *(const v4u*)(Vh + (size_t)(32 * (sb_) + 4 * vkg + i_) * 64 + 8 * vdc); } while (0)
; __device__ __forceinline__ void sb_attn(const bf16* QKV, bf16* O, LAS unsigned char* lds, int tid) {
;     ...
;     for (int u = gw; u < BATCH * 16 * (SEQ / 32); u += NGW) {
;         const int qblk = u & 127, bh = u >> 7, b = bh >> 4, h = bh & 15;
;         const size_t tok0 = (size_t)b * SEQ;
;         const int qr0 = qblk * 32, qpos = qr0 + l32;
;         bf16x8 qf[4], kn[4]; v4u vreg[4];
;         const bf16* const Qh = QKV + (size_t)(b * 48 + h) * SEQ * 64; const bf16* const Kh = QKV + (size_t)(b * 48 + 16 + h) * SEQ * 64; const bf16* const Vh = QKV + (size_t)(b * 48 + 32 + h) * SEQ * 64;
;         { const bf16* qp = Qh + (size_t)(qr0 + l32) * 64 + 8 * hi;
; #pragma unroll
;           for (int ks = 0; ks < 4; ++ks) qf[ks] = *(const bf16x8*)(qp + 16 * ks); }
;     ...
;         SBW_LOAD(qblk);
;         f32x16 o0, o1;
; #pragma unroll
;         for (int r = 0; r < 16; ++r) { o0[r] = 0.f; o1[r] = 0.f; }
;         float carry = 1.0f;
;         int p = 0;
;     ...
;             LAS unsigned char* vb = vimg;
; #pragma unroll
;             for (int j = 0; j < 4; ++j) *(LAS bf16x8*)(kimg + (8 * (2 * (j & 1) + (vkg >> 2)) + 4 * (j >> 1) + (vkg & 3)) * WK_ROW + 16 * vdc) = kn[j];
; #pragma unroll
;             for (int j = 0; j < 4; ++j) {
;                 const unsigned w0 = vreg[0][j], w1 = vreg[1][j], w2 = vreg[2][j], w3 = vreg[3][j];
;                 const u32x2 e = {(w0 & 0xffffu) | (w1 << 16), (w2 & 0xffffu) | (w3 << 16)};
;                 const u32x2 o = {(w0 >> 16) | (w1 & 0xffff0000u), (w2 >> 16) | (w3 & 0xffff0000u)};
;                 *(LAS u32x2*)(vb + (8 * vdc + 2 * j) * WV_ROW + 8 * vkg) = e; *(LAS u32x2*)(vb + (8 * vdc + 2 * j + 1) * WV_ROW + 8 * vkg) = o;
;             }
;             if (sb > 0) SBW_LOAD(sb - 1);
.LBB0_193:
	s_ashr_i32 s6, s8, 11
	s_bfe_u32 s10, s8, 0x40007
	s_mul_i32 s18, s6, 48
	s_or_b32 s12, s18, s10
	s_and_b32 s7, s8, 0x7f
	s_ashr_i32 s13, s12, 31
	s_lshl_b32 s11, s7, 5
	s_lshl_b64 s[14:15], s[12:13], 19
	s_add_u32 s14, s90, s14
	s_addc_u32 s15, s91, s15
	s_add_i32 s12, s12, 16
	s_ashr_i32 s13, s12, 31
	v_or_b32_e32 v16, s11, v96
	s_lshl_b64 s[16:17], s[12:13], 19
	s_add_i32 s12, s18, 32
	s_or_b32 s18, s12, s10
	v_lshlrev_b32_e32 v156, 7, v16
	s_ashr_i32 s19, s18, 31
	v_lshl_add_u64 v[0:1], s[14:15], 0, v[156:157]
	v_mov_b32_e32 v103, v157
	s_lshl_b64 s[18:19], s[18:19], 19
	v_lshl_add_u64 v[0:1], v[0:1], 0, v[102:103]
	global_load_dwordx4 v[48:51], v[0:1], off
	global_load_dwordx4 v[52:55], v[0:1], off offset:32
	global_load_dwordx4 v[56:59], v[0:1], off offset:64
	global_load_dwordx4 v[60:63], v[0:1], off offset:96
	s_add_u32 s14, s90, s16
	v_or_b32_e32 v0, s11, v97
	s_addc_u32 s15, s91, s17
	v_lshlrev_b32_e32 v156, 7, v0
	v_lshl_add_u64 v[0:1], s[14:15], 0, v[156:157]
	v_mov_b32_e32 v105, v157
	v_lshl_add_u64 v[0:1], v[0:1], 0, v[104:105]
	v_or_b32_e32 v2, s11, v112
	global_load_dwordx4 v[64:67], v[0:1], off
	global_load_dwordx4 v[68:71], v[0:1], off offset:1024
	global_load_dwordx4 v[72:75], v[0:1], off offset:2048
	global_load_dwordx4 v[76:79], v[0:1], off offset:3072
	v_lshl_add_u64 v[0:1], v[98:99], 0, s[18:19]
	v_lshlrev_b32_e32 v156, 7, v2
	v_lshl_add_u64 v[2:3], v[0:1], 0, v[156:157]
	global_load_dwordx4 v[80:83], v[2:3], off
	global_load_dwordx4 v[84:87], v[2:3], off offset:128
	global_load_dwordx4 v[88:91], v[2:3], off offset:256
	global_load_dwordx4 v[92:95], v[2:3], off offset:384
	v_lshl_add_u64 v[108:109], s[14:15], 0, v[104:105]
	s_add_i32 s13, s8, s67
	s_cmpk_gt_i32 s13, 0x3fff
	s_cselect_b32 s13, s8, s13
	s_ashr_i32 s16, s13, 11
	s_bfe_u32 s17, s13, 0x40007
	s_mul_i32 s16, s16, 48
	s_and_b32 s13, s13, 0x7f
	s_lshl_b32 s13, s13, 5
	s_or_b32 s18, s16, s17
	s_ashr_i32 s19, s18, 31
	s_lshl_b64 s[14:15], s[18:19], 19
	s_add_u32 s14, s90, s14
	s_addc_u32 s15, s91, s15
	v_or_b32_e32 v246, s13, v96
	v_lshlrev_b32_e32 v156, 7, v246
	v_lshl_add_u64 v[244:245], s[14:15], 0, v[156:157]
	v_lshl_add_u64 v[244:245], v[244:245], 0, v[102:103]
	global_load_dwordx4 v[128:131], v[244:245], off
	global_load_dwordx4 v[132:135], v[244:245], off offset:32
	global_load_dwordx4 v[136:139], v[244:245], off offset:64
	global_load_dwordx4 v[140:143], v[244:245], off offset:96
	s_add_i32 s18, s18, 16
	s_ashr_i32 s19, s18, 31
	s_lshl_b64 s[14:15], s[18:19], 19
	s_add_u32 s14, s90, s14
	s_addc_u32 s15, s91, s15
	v_or_b32_e32 v247, s13, v97
	v_lshlrev_b32_e32 v156, 7, v247
	v_lshl_add_u64 v[244:245], s[14:15], 0, v[156:157]
	v_lshl_add_u64 v[244:245], v[244:245], 0, v[104:105]
	global_load_dwordx4 v[144:147], v[244:245], off
	global_load_dwordx4 v[148:151], v[244:245], off offset:1024
	global_load_dwordx4 v[152:155], v[244:245], off offset:2048
	global_load_dwordx4 v[172:175], v[244:245], off offset:3072
	s_add_i32 s18, s16, 32
	s_or_b32 s18, s18, s17
	s_ashr_i32 s19, s18, 31
	s_lshl_b64 s[18:19], s[18:19], 19
	v_lshl_add_u64 v[244:245], v[98:99], 0, s[18:19]
	v_or_b32_e32 v247, s13, v112
	v_lshlrev_b32_e32 v156, 7, v247
	v_lshl_add_u64 v[248:249], v[244:245], 0, v[156:157]
	global_load_dwordx4 v[176:179], v[248:249], off
	global_load_dwordx4 v[180:183], v[248:249], off offset:128
	global_load_dwordx4 v[184:187], v[248:249], off offset:256
	global_load_dwordx4 v[188:191], v[248:249], off offset:384
	s_cmp_eq_u32 s7, 0
	s_waitcnt vmcnt(12)
.Lsb_cont:
	ds_write_b128 v116, v[64:67] offset:5120
	ds_write_b128 v116, v[68:71] offset:7424
	ds_write_b128 v117, v[72:75] offset:5120
	ds_write_b128 v118, v[76:79] offset:5120
	v_and_b32_e32 v2, 0xffff, v80
	v_lshrrev_b32_e32 v4, 16, v80
	v_and_b32_e32 v3, 0xffff, v88
	v_lshrrev_b32_e32 v5, 16, v88
	v_lshl_or_b32 v2, v84, 16, v2
	v_lshl_or_b32 v3, v92, 16, v3
	v_and_or_b32 v4, v84, s37, v4
	v_and_or_b32 v5, v92, s37, v5
	ds_write2_b64 v119, v[2:3], v[4:5] offset1:10
	v_and_b32_e32 v2, 0xffff, v81
	v_and_b32_e32 v3, 0xffff, v89
	v_lshrrev_b32_e32 v4, 16, v81
	v_lshrrev_b32_e32 v5, 16, v89
	v_lshl_or_b32 v2, v85, 16, v2
	v_lshl_or_b32 v3, v93, 16, v3
	v_and_or_b32 v4, v85, s37, v4
	v_and_or_b32 v5, v93, s37, v5
	ds_write2_b64 v119, v[2:3], v[4:5] offset0:20 offset1:30
	v_and_b32_e32 v2, 0xffff, v82
	v_and_b32_e32 v3, 0xffff, v90
	v_lshrrev_b32_e32 v4, 16, v82
	v_lshrrev_b32_e32 v5, 16, v90
	v_lshl_or_b32 v2, v86, 16, v2
	v_lshl_or_b32 v3, v94, 16, v3
	v_and_or_b32 v4, v86, s37, v4
	v_and_or_b32 v5, v94, s37, v5
	ds_write2_b64 v119, v[2:3], v[4:5] offset0:40 offset1:50
	v_and_b32_e32 v2, 0xffff, v83
	v_and_b32_e32 v3, 0xffff, v91
	v_lshrrev_b32_e32 v4, 16, v83
	v_lshrrev_b32_e32 v5, 16, v91
	v_lshl_or_b32 v2, v87, 16, v2
	v_lshl_or_b32 v3, v95, 16, v3
	v_and_or_b32 v4, v87, s37, v4
	v_and_or_b32 v5, v95, s37, v5
	ds_write2_b64 v119, v[2:3], v[4:5] offset0:60 offset1:70
	s_cbranch_scc1 .LBB0_195
	s_sub_i32 s13, s11, 32
	v_or_b32_e32 v156, s13, v97
	v_lshlrev_b64 v[2:3], 7, v[156:157]
	v_lshl_add_u64 v[2:3], v[108:109], 0, v[2:3]
	global_load_dwordx4 v[64:67], v[2:3], off
	global_load_dwordx4 v[68:71], v[2:3], off offset:1024
	global_load_dwordx4 v[72:75], v[2:3], off offset:2048
	global_load_dwordx4 v[76:79], v[2:3], off offset:3072
	v_or_b32_e32 v2, s13, v112
	v_ashrrev_i32_e32 v3, 31, v2
	v_or_b32_e32 v6, 1, v2
	v_lshlrev_b64 v[4:5], 7, v[2:3]
	v_ashrrev_i32_e32 v7, 31, v6
	v_lshl_add_u64 v[4:5], v[0:1], 0, v[4:5]
	v_lshlrev_b64 v[6:7], 7, v[6:7]
	v_lshl_add_u64 v[6:7], v[0:1], 0, v[6:7]
	global_load_dwordx4 v[80:83], v[4:5], off
	global_load_dwordx4 v[84:87], v[6:7], off
	v_or_b32_e32 v4, 2, v2
	v_ashrrev_i32_e32 v5, 31, v4
	v_or_b32_e32 v2, 3, v2
	v_lshlrev_b64 v[4:5], 7, v[4:5]
	v_ashrrev_i32_e32 v3, 31, v2
	v_lshl_add_u64 v[4:5], v[0:1], 0, v[4:5]
	v_lshlrev_b64 v[2:3], 7, v[2:3]
	v_lshl_add_u64 v[0:1], v[0:1], 0, v[2:3]
	global_load_dwordx4 v[88:91], v[4:5], off
	global_load_dwordx4 v[92:95], v[0:1], off
